# P10 main loop: wave priority raised while it holds the LDS accumulator lock (shorter hold, fewer retries)
# speedup vs baseline: 1.0005x; 1.0005x over previous
.Lcv_noprio:
	s_cmp_lt_u32 s4, 5
	s_cbranch_scc0 .Lcv_pre_skip
	v_add_u32_e32 v101, 0x16000, v100
	global_load_dwordx4 v[148:151], v101, s[62:63]
.Lcv_pre_skip:
	v_readlane_b32 s4, v254, 40
	s_waitcnt vmcnt(0)
	v_mov_b32_e32 v101, v100
	ds_write_b128 v101, v[104:107]
	v_add_u32_e32 v101, 0x2000, v100
	ds_write_b128 v101, v[108:111]
	v_add_u32_e32 v101, 0x4000, v100
	ds_write_b128 v101, v[112:115]
	v_add_u32_e32 v101, 0x6000, v100
	ds_write_b128 v101, v[116:119]
	v_add_u32_e32 v101, 0x8000, v100
	ds_write_b128 v101, v[120:123]
	v_add_u32_e32 v101, 0xa000, v100
	ds_write_b128 v101, v[124:127]
	v_add_u32_e32 v101, 0xc000, v100
	ds_write_b128 v101, v[128:131]
	v_add_u32_e32 v101, 0xe000, v100
	ds_write_b128 v101, v[132:135]
	v_add_u32_e32 v101, 0x10000, v100
	ds_write_b128 v101, v[136:139]
	v_add_u32_e32 v101, 0x12000, v100
	ds_write_b128 v101, v[140:143]
	v_add_u32_e32 v101, 0x14000, v100
	ds_write_b128 v101, v[144:147]
	s_cmp_lt_u32 s4, 5
	s_cbranch_scc0 .Lcv_pre_skip2
	v_add_u32_e32 v101, 0x16000, v100
	ds_write_b128 v101, v[148:151]

.Lq_locked_k0p0:
	s_setprio 3
	s_mov_b64 exec, s[54:55]
	ds_read_b128 v[82:85], v21
	ds_read_b128 v[86:89], v21 offset:32
	ds_read_b128 v[90:93], v21 offset:64
	ds_read_b128 v[94:97], v21 offset:96
	ds_read_b128 v[34:37], v21 offset:128
	ds_read_b128 v[38:41], v21 offset:160
	ds_read_b128 v[42:45], v21 offset:192
	ds_read_b128 v[46:49], v21 offset:224
	ds_read_b32 v28, v32
	s_waitcnt lgkmcnt(0)
	v_add_f32_e32 v82, v82, v66
	v_add_f32_e32 v83, v83, v67
	v_add_f32_e32 v84, v84, v68
	v_add_f32_e32 v85, v85, v69
	v_add_f32_e32 v86, v86, v70
	v_add_f32_e32 v87, v87, v71
	v_add_f32_e32 v88, v88, v72
	v_add_f32_e32 v89, v89, v73
	v_add_f32_e32 v90, v90, v74
	v_add_f32_e32 v91, v91, v75
	v_add_f32_e32 v92, v92, v76
	v_add_f32_e32 v93, v93, v77
	v_add_f32_e32 v94, v94, v78
	v_add_f32_e32 v95, v95, v79
	v_add_f32_e32 v96, v96, v80
	v_add_f32_e32 v97, v97, v81
	v_add_f32_e32 v34, v34, v50
	v_add_f32_e32 v35, v35, v51
	v_add_f32_e32 v36, v36, v52
	v_add_f32_e32 v37, v37, v53
	v_add_f32_e32 v38, v38, v54
	v_add_f32_e32 v39, v39, v55
	v_add_f32_e32 v40, v40, v56
	v_add_f32_e32 v41, v41, v57
	v_add_f32_e32 v42, v42, v58
	v_add_f32_e32 v43, v43, v59
	v_add_f32_e32 v44, v44, v60
	v_add_f32_e32 v45, v45, v61
	v_add_f32_e32 v46, v46, v62
	v_add_f32_e32 v47, v47, v63
	v_add_f32_e32 v48, v48, v64
	v_add_f32_e32 v49, v49, v65
	v_add_f32_e32 v28, v28, v221
	ds_write_b128 v21, v[82:85]
	ds_write_b128 v21, v[86:89] offset:32
	ds_write_b128 v21, v[90:93] offset:64
	ds_write_b128 v21, v[94:97] offset:96
	ds_write_b128 v21, v[34:37] offset:128
	ds_write_b128 v21, v[38:41] offset:160
	ds_write_b128 v21, v[42:45] offset:192
	ds_write_b128 v21, v[46:49] offset:224
	ds_write_b32 v32, v28
	s_mov_b64 exec, 1
	s_not_b64 s[64:65], s[60:61]
	v_mov_b32_e32 v16, s64
	v_mov_b32_e32 v17, s65
	ds_and_b64 v30, v[16:17]
	s_mov_b64 exec, s[58:59]
	s_setprio 0
	s_xor_b32 s93, s93, 1
	s_mov_b32 s68, s85
	s_cmp_lt_u32 s68, s86
	s_cbranch_scc1 .Lq_tk_k0
	s_branch .Lq_vend_k0
